# v108 + grid barrier: the XCD-local release word is written with a plain store (stays in the XCC's L2) instead of a memory-side atomic add
# speedup vs baseline: 1.0112x; 1.0030x over previous
.LBB0_152:
	s_or_b64 exec, exec, s[10:11]
	v_cvt_f32_u32_e32 v4, v2
	s_waitcnt vmcnt(0)
	v_readfirstlane_b32 s8, v3
	v_sub_u32_e32 v3, 0, v2
	v_rcp_iflag_f32_e32 v4, v4
	v_add_u32_e32 v5, s8, v1
	v_mul_f32_e32 v4, 0x4f7ffffe, v4
	v_cvt_u32_f32_e32 v4, v4
	v_mul_lo_u32 v1, v3, v4
	v_mul_hi_u32 v1, v4, v1
	v_add_u32_e32 v1, v4, v1
	v_mul_hi_u32 v1, v5, v1
	v_mul_lo_u32 v3, v1, v2
	v_sub_u32_e32 v3, v5, v3
	v_add_u32_e32 v4, 1, v1
	v_cmp_ge_u32_e32 vcc, v3, v2
	s_nop 1
	v_cndmask_b32_e32 v1, v1, v4, vcc
	v_sub_u32_e32 v4, v3, v2
	v_cndmask_b32_e32 v3, v3, v4, vcc
	v_add_u32_e32 v4, 1, v1
	v_cmp_ge_u32_e32 vcc, v3, v2
	v_add_u32_e32 v3, 1, v5
	s_nop 0
	v_cndmask_b32_e32 v1, v1, v4, vcc
	v_mul_lo_u32 v4, v2, v1
	v_readfirstlane_b32 s99, v1
	v_add_u32_e32 v2, v4, v2
	v_cmp_ne_u32_e32 vcc, v3, v2
	s_and_saveexec_b64 s[8:9], vcc
	s_xor_b64 s[8:9], exec, s[8:9]
	s_cbranch_execz .LBB0_166
	s_waitcnt lgkmcnt(0)
	buffer_inv sc1
	v_mov_b32_e32 v0, 0x2000
	global_load_dword v0, v0, s[6:7] offset:1024 sc1
	s_add_u32 s22, s6, 0x2400
	s_addc_u32 s23, s7, 0
	s_waitcnt vmcnt(0)
	v_cmp_eq_u32_e32 vcc, v0, v1
	s_and_saveexec_b64 s[10:11], vcc
	s_cbranch_execz .LBB0_165
	s_add_u32 s20, s40, 0x4200
	s_addc_u32 s21, s41, 0
	s_mov_b32 s26, 1
	s_mov_b64 s[24:25], 0
	v_mov_b32_e32 v0, 0
	s_branch .LBB0_156

.LBB0_183:
	s_or_b64 exec, exec, s[8:9]
	s_mov_b64 s[8:9], exec
	v_mbcnt_lo_u32_b32 v0, s8, 0
	v_mbcnt_hi_u32_b32 v0, s9, v0
	v_cmp_eq_u32_e32 vcc, 0, v0
	s_waitcnt vmcnt(0)
	s_and_saveexec_b64 s[10:11], vcc
	s_cbranch_execz .LBB0_185
	s_bcnt1_i32_b64 s8, s[8:9]
	v_mov_b32_e32 v0, 0x2000
	s_add_i32 s99, s99, 1
	v_mov_b32_e32 v1, s99
	global_store_dword v0, v1, s[6:7] offset:1024

.LBB0_361:
	s_or_b64 exec, exec, s[10:11]
	v_cvt_f32_u32_e32 v4, v2
	s_waitcnt vmcnt(0)
	v_readfirstlane_b32 s8, v3
	v_sub_u32_e32 v3, 0, v2
	v_rcp_iflag_f32_e32 v4, v4
	v_add_u32_e32 v5, s8, v1
	v_mul_f32_e32 v4, 0x4f7ffffe, v4
	v_cvt_u32_f32_e32 v4, v4
	v_mul_lo_u32 v1, v3, v4
	v_mul_hi_u32 v1, v4, v1
	v_add_u32_e32 v1, v4, v1
	v_mul_hi_u32 v1, v5, v1
	v_mul_lo_u32 v3, v1, v2
	v_sub_u32_e32 v3, v5, v3
	v_add_u32_e32 v4, 1, v1
	v_cmp_ge_u32_e32 vcc, v3, v2
	s_nop 1
	v_cndmask_b32_e32 v1, v1, v4, vcc
	v_sub_u32_e32 v4, v3, v2
	v_cndmask_b32_e32 v3, v3, v4, vcc
	v_add_u32_e32 v4, 1, v1
	v_cmp_ge_u32_e32 vcc, v3, v2
	v_add_u32_e32 v3, 1, v5
	s_nop 0
	v_cndmask_b32_e32 v1, v1, v4, vcc
	v_mul_lo_u32 v4, v2, v1
	v_readfirstlane_b32 s99, v1
	v_add_u32_e32 v2, v4, v2
	v_cmp_ne_u32_e32 vcc, v3, v2
	s_and_saveexec_b64 s[8:9], vcc
	s_xor_b64 s[8:9], exec, s[8:9]
	s_cbranch_execz .LBB0_375
	s_waitcnt lgkmcnt(0)
	buffer_inv sc1
	v_mov_b32_e32 v0, 0x2000
	global_load_dword v0, v0, s[6:7] offset:1024 sc1
	s_add_u32 s16, s6, 0x2400
	s_addc_u32 s17, s7, 0
	s_waitcnt vmcnt(0)
	v_cmp_eq_u32_e32 vcc, v0, v1
	s_and_saveexec_b64 s[10:11], vcc
	s_cbranch_execz .LBB0_374
	s_add_u32 s14, s40, 0x4200
	s_addc_u32 s15, s41, 0
	s_mov_b32 s26, 1
	s_mov_b64 s[18:19], 0
	v_mov_b32_e32 v0, 0
	s_branch .LBB0_365

.LBB0_639:
	s_or_b64 exec, exec, s[10:11]
	v_cvt_f32_u32_e32 v4, v2
	s_waitcnt vmcnt(0)
	v_readfirstlane_b32 s8, v3
	v_sub_u32_e32 v3, 0, v2
	v_rcp_iflag_f32_e32 v4, v4
	v_add_u32_e32 v5, s8, v1
	v_mul_f32_e32 v4, 0x4f7ffffe, v4
	v_cvt_u32_f32_e32 v4, v4
	v_mul_lo_u32 v1, v3, v4
	v_mul_hi_u32 v1, v4, v1
	v_add_u32_e32 v1, v4, v1
	v_mul_hi_u32 v1, v5, v1
	v_mul_lo_u32 v3, v1, v2
	v_sub_u32_e32 v3, v5, v3
	v_add_u32_e32 v4, 1, v1
	v_cmp_ge_u32_e32 vcc, v3, v2
	s_nop 1
	v_cndmask_b32_e32 v1, v1, v4, vcc
	v_sub_u32_e32 v4, v3, v2
	v_cndmask_b32_e32 v3, v3, v4, vcc
	v_add_u32_e32 v4, 1, v1
	v_cmp_ge_u32_e32 vcc, v3, v2
	v_add_u32_e32 v3, 1, v5
	s_nop 0
	v_cndmask_b32_e32 v1, v1, v4, vcc
	v_mul_lo_u32 v4, v2, v1
	v_readfirstlane_b32 s99, v1
	v_add_u32_e32 v2, v4, v2
	v_cmp_ne_u32_e32 vcc, v3, v2
	s_and_saveexec_b64 s[8:9], vcc
	s_xor_b64 s[8:9], exec, s[8:9]
	s_cbranch_execz .LBB0_653
	s_waitcnt lgkmcnt(0)
	buffer_inv sc1
	v_mov_b32_e32 v0, 0x2000
	global_load_dword v0, v0, s[6:7] offset:1024 sc1
	s_add_u32 s16, s6, 0x2400
	s_addc_u32 s17, s7, 0
	s_waitcnt vmcnt(0)
	v_cmp_eq_u32_e32 vcc, v0, v1
	s_and_saveexec_b64 s[10:11], vcc
	s_cbranch_execz .LBB0_652
	s_add_u32 s12, s40, 0x4200
	s_addc_u32 s13, s41, 0
	s_mov_b32 s26, 1
	s_mov_b64 s[18:19], 0
	v_mov_b32_e32 v0, 0
	s_branch .LBB0_643

.LBB0_747:
	s_or_b64 exec, exec, s[10:11]
	v_cvt_f32_u32_e32 v4, v2
	s_waitcnt vmcnt(0)
	v_readfirstlane_b32 s8, v3
	v_sub_u32_e32 v3, 0, v2
	v_rcp_iflag_f32_e32 v4, v4
	v_add_u32_e32 v5, s8, v1
	v_mul_f32_e32 v4, 0x4f7ffffe, v4
	v_cvt_u32_f32_e32 v4, v4
	v_mul_lo_u32 v1, v3, v4
	v_mul_hi_u32 v1, v4, v1
	v_add_u32_e32 v1, v4, v1
	v_mul_hi_u32 v1, v5, v1
	v_mul_lo_u32 v3, v1, v2
	v_sub_u32_e32 v3, v5, v3
	v_add_u32_e32 v4, 1, v1
	v_cmp_ge_u32_e32 vcc, v3, v2
	s_nop 1
	v_cndmask_b32_e32 v1, v1, v4, vcc
	v_sub_u32_e32 v4, v3, v2
	v_cndmask_b32_e32 v3, v3, v4, vcc
	v_add_u32_e32 v4, 1, v1
	v_cmp_ge_u32_e32 vcc, v3, v2
	v_add_u32_e32 v3, 1, v5
	s_nop 0
	v_cndmask_b32_e32 v1, v1, v4, vcc
	v_mul_lo_u32 v4, v2, v1
	v_readfirstlane_b32 s99, v1
	v_add_u32_e32 v2, v4, v2
	v_cmp_ne_u32_e32 vcc, v3, v2
	s_and_saveexec_b64 s[8:9], vcc
	s_xor_b64 s[8:9], exec, s[8:9]
	s_cbranch_execz .LBB0_761
	s_waitcnt lgkmcnt(0)
	buffer_inv sc1
	v_mov_b32_e32 v0, 0x2000
	global_load_dword v0, v0, s[6:7] offset:1024 sc1
	s_add_u32 s14, s6, 0x2400
	s_addc_u32 s15, s7, 0
	s_waitcnt vmcnt(0)
	v_cmp_eq_u32_e32 vcc, v0, v1
	s_and_saveexec_b64 s[10:11], vcc
	s_cbranch_execz .LBB0_760
	s_add_u32 s12, s40, 0x4200
	s_addc_u32 s13, s41, 0
	s_mov_b32 s26, 1
	s_mov_b64 s[16:17], 0
	v_mov_b32_e32 v0, 0
	s_branch .LBB0_751

.LBB0_886:
	s_or_b64 exec, exec, s[12:13]
	v_cvt_f32_u32_e32 v38, v36
	s_waitcnt vmcnt(0)
	v_readfirstlane_b32 s10, v37
	v_sub_u32_e32 v37, 0, v36
	v_rcp_iflag_f32_e32 v38, v38
	v_add_u32_e32 v39, s10, v33
	v_mul_f32_e32 v38, 0x4f7ffffe, v38
	v_cvt_u32_f32_e32 v38, v38
	v_mul_lo_u32 v33, v37, v38
	v_mul_hi_u32 v33, v38, v33
	v_add_u32_e32 v33, v38, v33
	v_mul_hi_u32 v33, v39, v33
	v_mul_lo_u32 v37, v33, v36
	v_sub_u32_e32 v37, v39, v37
	v_add_u32_e32 v38, 1, v33
	v_cmp_ge_u32_e32 vcc, v37, v36
	s_nop 1
	v_cndmask_b32_e32 v33, v33, v38, vcc
	v_sub_u32_e32 v38, v37, v36
	v_cndmask_b32_e32 v37, v37, v38, vcc
	v_add_u32_e32 v38, 1, v33
	v_cmp_ge_u32_e32 vcc, v37, v36
	v_add_u32_e32 v37, 1, v39
	s_nop 0
	v_cndmask_b32_e32 v33, v33, v38, vcc
	v_mul_lo_u32 v38, v36, v33
	v_readfirstlane_b32 s99, v33
	v_add_u32_e32 v36, v38, v36
	v_cmp_ne_u32_e32 vcc, v37, v36
	s_and_saveexec_b64 s[10:11], vcc
	s_xor_b64 s[10:11], exec, s[10:11]
	s_cbranch_execz .LBB0_900
	s_waitcnt lgkmcnt(0)
	buffer_inv sc1
	v_mov_b32_e32 v32, 0x2000
	global_load_dword v32, v32, s[8:9] offset:1024 sc1
	s_add_u32 s16, s8, 0x2400
	s_addc_u32 s17, s9, 0
	s_waitcnt vmcnt(0)
	v_cmp_eq_u32_e32 vcc, v32, v33
	s_and_saveexec_b64 s[12:13], vcc
	s_cbranch_execz .LBB0_899
	s_add_u32 s14, s40, 0x4200
	s_addc_u32 s15, s41, 0
	s_mov_b32 s28, 1
	s_mov_b64 s[18:19], 0
	v_mov_b32_e32 v32, 0
	s_branch .LBB0_890

.LBB0_917:
	s_or_b64 exec, exec, s[10:11]
	s_mov_b64 s[10:11], exec
	v_mbcnt_lo_u32_b32 v32, s10, 0
	v_mbcnt_hi_u32_b32 v32, s11, v32
	v_cmp_eq_u32_e32 vcc, 0, v32
	s_waitcnt vmcnt(0)
	s_and_saveexec_b64 s[12:13], vcc
	s_cbranch_execz .LBB0_919
	s_bcnt1_i32_b64 s10, s[10:11]
	v_mov_b32_e32 v32, 0x2000
	s_add_i32 s99, s99, 1
	v_mov_b32_e32 v33, s99
	global_store_dword v32, v33, s[8:9] offset:1024

.LBB0_972:
	s_or_b64 exec, exec, s[12:13]
	v_cvt_f32_u32_e32 v4, v2
	s_waitcnt vmcnt(0)
	v_readfirstlane_b32 s8, v3
	v_sub_u32_e32 v3, 0, v2
	v_rcp_iflag_f32_e32 v4, v4
	v_add_u32_e32 v5, s8, v1
	v_mul_f32_e32 v4, 0x4f7ffffe, v4
	v_cvt_u32_f32_e32 v4, v4
	v_mul_lo_u32 v1, v3, v4
	v_mul_hi_u32 v1, v4, v1
	v_add_u32_e32 v1, v4, v1
	v_mul_hi_u32 v1, v5, v1
	v_mul_lo_u32 v3, v1, v2
	v_sub_u32_e32 v3, v5, v3
	v_add_u32_e32 v4, 1, v1
	v_cmp_ge_u32_e32 vcc, v3, v2
	s_nop 1
	v_cndmask_b32_e32 v1, v1, v4, vcc
	v_sub_u32_e32 v4, v3, v2
	v_cndmask_b32_e32 v3, v3, v4, vcc
	v_add_u32_e32 v4, 1, v1
	v_cmp_ge_u32_e32 vcc, v3, v2
	v_add_u32_e32 v3, 1, v5
	s_nop 0
	v_cndmask_b32_e32 v1, v1, v4, vcc
	v_mul_lo_u32 v4, v2, v1
	v_readfirstlane_b32 s99, v1
	v_add_u32_e32 v2, v4, v2
	v_cmp_ne_u32_e32 vcc, v3, v2
	s_and_saveexec_b64 s[8:9], vcc
	s_xor_b64 s[8:9], exec, s[8:9]
	s_cbranch_execz .LBB0_986
	s_waitcnt lgkmcnt(0)
	buffer_inv sc1
	v_mov_b32_e32 v0, 0x2000
	global_load_dword v0, v0, s[6:7] offset:1024 sc1
	s_add_u32 s16, s6, 0x2400
	s_addc_u32 s17, s7, 0
	s_waitcnt vmcnt(0)
	v_cmp_eq_u32_e32 vcc, v0, v1
	s_and_saveexec_b64 s[12:13], vcc
	s_cbranch_execz .LBB0_985
	s_add_u32 s14, s40, 0x4200
	s_addc_u32 s15, s41, 0
	s_mov_b32 s28, 1
	s_mov_b64 s[18:19], 0
	v_mov_b32_e32 v0, 0
	s_branch .LBB0_976

.LBB0_1003:
	s_or_b64 exec, exec, s[8:9]
	s_mov_b64 s[8:9], exec
	v_mbcnt_lo_u32_b32 v0, s8, 0
	v_mbcnt_hi_u32_b32 v0, s9, v0
	v_cmp_eq_u32_e32 vcc, 0, v0
	s_waitcnt vmcnt(0)
	s_and_saveexec_b64 s[12:13], vcc
	s_cbranch_execz .LBB0_1005
	s_bcnt1_i32_b64 s8, s[8:9]
	v_mov_b32_e32 v0, 0x2000
	s_add_i32 s99, s99, 1
	v_mov_b32_e32 v1, s99
	global_store_dword v0, v1, s[6:7] offset:1024

.LBB0_1078:
	s_or_b64 exec, exec, s[14:15]
	v_cvt_f32_u32_e32 v4, v2
	s_waitcnt vmcnt(0)
	v_readfirstlane_b32 s12, v3
	v_sub_u32_e32 v3, 0, v2
	v_rcp_iflag_f32_e32 v4, v4
	v_add_u32_e32 v5, s12, v1
	v_mul_f32_e32 v4, 0x4f7ffffe, v4
	v_cvt_u32_f32_e32 v4, v4
	v_mul_lo_u32 v1, v3, v4
	v_mul_hi_u32 v1, v4, v1
	v_add_u32_e32 v1, v4, v1
	v_mul_hi_u32 v1, v5, v1
	v_mul_lo_u32 v3, v1, v2
	v_sub_u32_e32 v3, v5, v3
	v_add_u32_e32 v4, 1, v1
	v_cmp_ge_u32_e32 vcc, v3, v2
	s_nop 1
	v_cndmask_b32_e32 v1, v1, v4, vcc
	v_sub_u32_e32 v4, v3, v2
	v_cndmask_b32_e32 v3, v3, v4, vcc
	v_add_u32_e32 v4, 1, v1
	v_cmp_ge_u32_e32 vcc, v3, v2
	v_add_u32_e32 v3, 1, v5
	s_nop 0
	v_cndmask_b32_e32 v1, v1, v4, vcc
	v_mul_lo_u32 v4, v2, v1
	v_readfirstlane_b32 s99, v1
	v_add_u32_e32 v2, v4, v2
	v_cmp_ne_u32_e32 vcc, v3, v2
	s_and_saveexec_b64 s[12:13], vcc
	s_xor_b64 s[12:13], exec, s[12:13]
	s_cbranch_execz .LBB0_1092
	s_waitcnt lgkmcnt(0)
	buffer_inv sc1
	v_mov_b32_e32 v0, 0x2000
	global_load_dword v0, v0, s[10:11] offset:1024 sc1
	s_add_u32 s20, s10, 0x2400
	s_addc_u32 s21, s11, 0
	s_waitcnt vmcnt(0)
	v_cmp_eq_u32_e32 vcc, v0, v1
	s_and_saveexec_b64 s[14:15], vcc
	s_cbranch_execz .LBB0_1091
	s_add_u32 s16, s40, 0x4200
	s_addc_u32 s17, s41, 0
	s_mov_b32 s34, 1
	s_mov_b64 s[22:23], 0
	v_mov_b32_e32 v0, 0
	s_branch .LBB0_1082

.LBB0_1109:
	s_or_b64 exec, exec, s[12:13]
	s_mov_b64 s[12:13], exec
	v_mbcnt_lo_u32_b32 v0, s12, 0
	v_mbcnt_hi_u32_b32 v0, s13, v0
	v_cmp_eq_u32_e32 vcc, 0, v0
	s_waitcnt vmcnt(0)
	s_and_saveexec_b64 s[14:15], vcc
	s_cbranch_execz .LBB0_1111
	s_bcnt1_i32_b64 s12, s[12:13]
	v_mov_b32_e32 v0, 0x2000
	s_add_i32 s99, s99, 1
	v_mov_b32_e32 v1, s99
	global_store_dword v0, v1, s[10:11] offset:1024

.LBB0_1196:
	s_or_b64 exec, exec, s[10:11]
	v_cvt_f32_u32_e32 v4, v2
	s_waitcnt vmcnt(0)
	v_readfirstlane_b32 s8, v3
	v_sub_u32_e32 v3, 0, v2
	v_rcp_iflag_f32_e32 v4, v4
	v_add_u32_e32 v5, s8, v1
	v_mul_f32_e32 v4, 0x4f7ffffe, v4
	v_cvt_u32_f32_e32 v4, v4
	v_mul_lo_u32 v1, v3, v4
	v_mul_hi_u32 v1, v4, v1
	v_add_u32_e32 v1, v4, v1
	v_mul_hi_u32 v1, v5, v1
	v_mul_lo_u32 v3, v1, v2
	v_sub_u32_e32 v3, v5, v3
	v_add_u32_e32 v4, 1, v1
	v_cmp_ge_u32_e32 vcc, v3, v2
	s_nop 1
	v_cndmask_b32_e32 v1, v1, v4, vcc
	v_sub_u32_e32 v4, v3, v2
	v_cndmask_b32_e32 v3, v3, v4, vcc
	v_add_u32_e32 v4, 1, v1
	v_cmp_ge_u32_e32 vcc, v3, v2
	v_add_u32_e32 v3, 1, v5
	s_nop 0
	v_cndmask_b32_e32 v1, v1, v4, vcc
	v_mul_lo_u32 v4, v2, v1
	v_readfirstlane_b32 s99, v1
	v_add_u32_e32 v2, v4, v2
	v_cmp_ne_u32_e32 vcc, v3, v2
	s_and_saveexec_b64 s[8:9], vcc
	s_xor_b64 s[8:9], exec, s[8:9]
	s_cbranch_execz .LBB0_1210
	s_waitcnt lgkmcnt(0)
	buffer_inv sc1
	v_mov_b32_e32 v0, 0x2000
	global_load_dword v0, v0, s[6:7] offset:1024 sc1
	s_add_u32 s16, s6, 0x2400
	s_addc_u32 s17, s7, 0
	s_waitcnt vmcnt(0)
	v_cmp_eq_u32_e32 vcc, v0, v1
	s_and_saveexec_b64 s[10:11], vcc
	s_cbranch_execz .LBB0_1209
	s_add_u32 s14, s40, 0x4200
	s_addc_u32 s15, s41, 0
	s_mov_b32 s30, 1
	s_mov_b64 s[20:21], 0
	v_mov_b32_e32 v0, 0
	s_branch .LBB0_1200

.LBB0_1305:
	s_or_b64 exec, exec, s[10:11]
	v_cvt_f32_u32_e32 v4, v2
	s_waitcnt vmcnt(0)
	v_readfirstlane_b32 s3, v3
	v_sub_u32_e32 v3, 0, v2
	v_rcp_iflag_f32_e32 v4, v4
	v_add_u32_e32 v5, s3, v1
	v_mul_f32_e32 v4, 0x4f7ffffe, v4
	v_cvt_u32_f32_e32 v4, v4
	v_mul_lo_u32 v1, v3, v4
	v_mul_hi_u32 v1, v4, v1
	v_add_u32_e32 v1, v4, v1
	v_mul_hi_u32 v1, v5, v1
	v_mul_lo_u32 v3, v1, v2
	v_sub_u32_e32 v3, v5, v3
	v_add_u32_e32 v4, 1, v1
	v_cmp_ge_u32_e32 vcc, v3, v2
	s_nop 1
	v_cndmask_b32_e32 v1, v1, v4, vcc
	v_sub_u32_e32 v4, v3, v2
	v_cndmask_b32_e32 v3, v3, v4, vcc
	v_add_u32_e32 v4, 1, v1
	v_cmp_ge_u32_e32 vcc, v3, v2
	v_add_u32_e32 v3, 1, v5
	s_nop 0
	v_cndmask_b32_e32 v1, v1, v4, vcc
	v_mul_lo_u32 v4, v2, v1
	v_readfirstlane_b32 s99, v1
	v_add_u32_e32 v2, v4, v2
	v_cmp_ne_u32_e32 vcc, v3, v2
	s_and_saveexec_b64 s[8:9], vcc
	s_xor_b64 s[8:9], exec, s[8:9]
	s_cbranch_execz .LBB0_1319
	s_waitcnt lgkmcnt(0)
	buffer_inv sc1
	v_mov_b32_e32 v0, 0x2000
	global_load_dword v0, v0, s[6:7] offset:1024 sc1
	s_add_u32 s14, s6, 0x2400
	s_addc_u32 s15, s7, 0
	s_waitcnt vmcnt(0)
	v_cmp_eq_u32_e32 vcc, v0, v1
	s_and_saveexec_b64 s[10:11], vcc
	s_cbranch_execz .LBB0_1318
	s_add_u32 s12, s40, 0x4200
	s_addc_u32 s13, s41, 0
	s_mov_b32 s3, 1
	s_mov_b64 s[16:17], 0
	v_mov_b32_e32 v0, 0
	s_branch .LBB0_1309

.LBB0_1336:
	s_or_b64 exec, exec, s[8:9]
	s_mov_b64 s[8:9], exec
	v_mbcnt_lo_u32_b32 v0, s8, 0
	v_mbcnt_hi_u32_b32 v0, s9, v0
	v_cmp_eq_u32_e32 vcc, 0, v0
	s_waitcnt vmcnt(0)
	s_and_saveexec_b64 s[10:11], vcc
	s_cbranch_execz .LBB0_1338
	s_bcnt1_i32_b64 s3, s[8:9]
	v_mov_b32_e32 v0, 0x2000
	s_add_i32 s99, s99, 1
	v_mov_b32_e32 v1, s99
	global_store_dword v0, v1, s[6:7] offset:1024
